# placement trial: MLA tile loop alone shifted by 8 bytes (later loops unchanged)
# speedup vs baseline: 1.0038x; 1.0011x over previous
; DI float xhalf_sum(float m) { auto rr = __builtin_amdgcn_permlane32_swap(__float_as_uint(m), __float_as_uint(m), false, false); return __uint_as_float(rr[0]) + __uint_as_float(rr[1]); }
; template <int DQK, int DV, bool CAUSAL, int KT, bool PRIO>
; DI void attn_unit(const bf16_t* Qb, int qpitch, const bf16_t* Kb, int kpitch, const bf16_t* Vtb, int vpitch, bf16_t* Ob, int opitch, int q0, int nt, LAS unsigned char* lds, float kbound, const float* qgain, const int* qpos, float qscale) {
;     ...
;         float q2 = 0.f;
; #pragma unroll
;         for (int ks = 0; ks < DQK / 16; ++ks)
; #pragma unroll
;             for (int e = 0; e < 8; ++e) { const float v = __uint_as_float(((unsigned)(unsigned short)qf[ks][e]) << 16); q2 += v * v; }
;         q2 = xhalf_sum(q2);
;         nomax = __all(sqrtf(q2) * kbound <= 100.0f) != 0;
.LBB0_1486:
	s_waitcnt vmcnt(0) lgkmcnt(0)
	v_and_b32_e32 v9, 0xffff0000, v116
	v_lshlrev_b32_e32 v8, 16, v116
	v_mul_f32_e32 v11, v9, v9
	v_fmac_f32_e32 v11, v8, v8
	v_lshlrev_b32_e32 v8, 16, v117
	v_fmac_f32_e32 v11, v8, v8
	v_and_b32_e32 v8, 0xffff0000, v117
	v_fmac_f32_e32 v11, v8, v8
	v_lshlrev_b32_e32 v8, 16, v118
	v_fmac_f32_e32 v11, v8, v8
	v_and_b32_e32 v8, 0xffff0000, v118
	v_fmac_f32_e32 v11, v8, v8
	v_lshlrev_b32_e32 v8, 16, v119
	v_fmac_f32_e32 v11, v8, v8
	v_and_b32_e32 v8, 0xffff0000, v119
	v_fmac_f32_e32 v11, v8, v8
	v_lshlrev_b32_e32 v8, 16, v120
	v_fmac_f32_e32 v11, v8, v8
	v_and_b32_e32 v8, 0xffff0000, v120
	v_fmac_f32_e32 v11, v8, v8
	v_lshlrev_b32_e32 v8, 16, v121
	v_fmac_f32_e32 v11, v8, v8
	v_and_b32_e32 v8, 0xffff0000, v121
	v_fmac_f32_e32 v11, v8, v8
	v_lshlrev_b32_e32 v8, 16, v122
	v_fmac_f32_e32 v11, v8, v8
	v_and_b32_e32 v8, 0xffff0000, v122
	v_fmac_f32_e32 v11, v8, v8
	v_lshlrev_b32_e32 v8, 16, v123
	v_fmac_f32_e32 v11, v8, v8
	v_and_b32_e32 v8, 0xffff0000, v123
	v_fmac_f32_e32 v11, v8, v8
	v_lshlrev_b32_e32 v8, 16, v124
	v_fmac_f32_e32 v11, v8, v8
	v_and_b32_e32 v8, 0xffff0000, v124
	v_fmac_f32_e32 v11, v8, v8
	v_lshlrev_b32_e32 v8, 16, v125
	v_fmac_f32_e32 v11, v8, v8
	v_and_b32_e32 v8, 0xffff0000, v125
	v_fmac_f32_e32 v11, v8, v8
	v_lshlrev_b32_e32 v8, 16, v126
	v_fmac_f32_e32 v11, v8, v8
	v_and_b32_e32 v8, 0xffff0000, v126
	v_fmac_f32_e32 v11, v8, v8
	v_lshlrev_b32_e32 v8, 16, v127
	v_fmac_f32_e32 v11, v8, v8
	v_and_b32_e32 v8, 0xffff0000, v127
	v_fmac_f32_e32 v11, v8, v8
	v_lshlrev_b32_e32 v8, 16, v128
	v_fmac_f32_e32 v11, v8, v8
	v_and_b32_e32 v8, 0xffff0000, v128
	v_fmac_f32_e32 v11, v8, v8
	v_lshlrev_b32_e32 v8, 16, v129
	v_fmac_f32_e32 v11, v8, v8
	v_and_b32_e32 v8, 0xffff0000, v129
	v_fmac_f32_e32 v11, v8, v8
	v_lshlrev_b32_e32 v8, 16, v130
	v_fmac_f32_e32 v11, v8, v8
	v_and_b32_e32 v8, 0xffff0000, v130
	v_fmac_f32_e32 v11, v8, v8
	v_lshlrev_b32_e32 v8, 16, v131
	v_fmac_f32_e32 v11, v8, v8
	v_and_b32_e32 v8, 0xffff0000, v131
	v_fmac_f32_e32 v11, v8, v8
	v_lshlrev_b32_e32 v8, 16, v132
	v_fmac_f32_e32 v11, v8, v8
	v_and_b32_e32 v8, 0xffff0000, v132
	v_fmac_f32_e32 v11, v8, v8
	v_lshlrev_b32_e32 v8, 16, v133
	v_fmac_f32_e32 v11, v8, v8
	v_and_b32_e32 v8, 0xffff0000, v133
	v_fmac_f32_e32 v11, v8, v8
	v_lshlrev_b32_e32 v8, 16, v134
	v_fmac_f32_e32 v11, v8, v8
	v_and_b32_e32 v8, 0xffff0000, v134
	v_fmac_f32_e32 v11, v8, v8
	v_lshlrev_b32_e32 v8, 16, v135
	v_fmac_f32_e32 v11, v8, v8
	v_and_b32_e32 v8, 0xffff0000, v135
	v_fmac_f32_e32 v11, v8, v8
	v_lshlrev_b32_e32 v8, 16, v136
	v_fmac_f32_e32 v11, v8, v8
	v_and_b32_e32 v8, 0xffff0000, v136
	v_fmac_f32_e32 v11, v8, v8
	v_and_b32_e32 v9, 0xffff0000, v137
	v_lshlrev_b32_e32 v8, 16, v137
	v_pk_mul_f32 v[8:9], v[8:9], v[8:9]
	s_xor_b64 s[34:35], s[2:3], -1
	v_add_f32_e32 v8, v8, v11
	v_add_f32_e32 v11, v9, v8
	v_and_b32_e32 v9, 0xffff0000, v138
	v_lshlrev_b32_e32 v8, 16, v138
	v_pk_mul_f32 v[8:9], v[8:9], v[8:9]
	v_mad_i64_i32 v[2:3], s[2:3], v149, s88, 0
	v_add_f32_e32 v8, v8, v11
	v_add_f32_e32 v11, v9, v8
	v_and_b32_e32 v9, 0xffff0000, v139
	v_lshlrev_b32_e32 v8, 16, v139
	v_pk_mul_f32 v[8:9], v[8:9], v[8:9]
	v_mad_i64_i32 v[4:5], s[2:3], v151, s88, 0
	v_add_f32_e32 v8, v8, v11
	v_add_f32_e32 v8, v9, v8
	v_mov_b32_e32 v9, v8
	s_nop 1
	v_permlane32_swap_b32_e32 v8, v9
	v_add_f32_e32 v8, v8, v9
	v_mul_f32_e32 v9, 0x4f800000, v8
	v_cmp_gt_f32_e32 vcc, s91, v8
	v_mad_i64_i32 v[6:7], s[2:3], v153, s88, 0
	s_nop 0
	v_cndmask_b32_e32 v8, v8, v9, vcc
	v_sqrt_f32_e32 v9, v8
	s_add_i32 s2, s38, 0x100
	s_lshr_b32 s68, s2, 7
	v_mul_lo_u32 v178, v149, s53
	v_add_u32_e32 v11, -1, v9
	v_fma_f32 v12, -v11, v9, v8
	v_cmp_ge_f32_e64 s[2:3], 0, v12
; DI float xhalf_sum(float m) { auto rr = __builtin_amdgcn_permlane32_swap(__float_as_uint(m), __float_as_uint(m), false, false); return __uint_as_float(rr[0]) + __uint_as_float(rr[1]); }
; template <int DQK, int DV, bool CAUSAL, int KT, bool PRIO>
; DI void attn_unit(const bf16_t* Qb, int qpitch, const bf16_t* Kb, int kpitch, const bf16_t* Vtb, int vpitch, bf16_t* Ob, int opitch, int q0, int nt, LAS unsigned char* lds, float kbound, const float* qgain, const int* qpos, float qscale) {
;     ...
;     f32x16 o[DV / 32], negm;
; #pragma unroll
;     for (int i = 0; i < 16; ++i) negm[i] = 0.f;
; #pragma unroll
;     for (int d = 0; d < DV / 32; ++d)
; #pragma unroll
;         for (int i = 0; i < 16; ++i) o[d][i] = 0.f;
;     float mrun = 0.f, lrun = 0.f; bool first = true;
;     bool nomax = false;
;     if (PRIO) {
;         float q2 = 0.f;
; #pragma unroll
;         for (int ks = 0; ks < DQK / 16; ++ks)
; #pragma unroll
;             for (int e = 0; e < 8; ++e) { const float v = __uint_as_float(((unsigned)(unsigned short)qf[ks][e]) << 16); q2 += v * v; }
;         q2 = xhalf_sum(q2);
;         nomax = __all(sqrtf(q2) * kbound <= 100.0f) != 0;
;     }
;     lstore(0);
;     __syncthreads();
;     const int qabs = q0 + 32 * w + r, qlo = q0 + 32 * w;
	v_add_u32_e32 v12, 1, v9
	v_lshlrev_b32_e32 v179, 4, v150
	v_cndmask_b32_e64 v11, v9, v11, s[2:3]
	v_fma_f32 v9, -v12, v9, v8
	v_cmp_lt_f32_e64 s[2:3], 0, v9
	v_mul_lo_u32 v181, v151, s53
	v_lshlrev_b32_e32 v182, 4, v152
	v_cndmask_b32_e64 v9, v11, v12, s[2:3]
	v_mul_f32_e32 v11, 0x37800000, v9
	v_cndmask_b32_e32 v9, v9, v11, vcc
	v_cmp_class_f32_e32 vcc, v8, v176
	v_mul_lo_u32 v183, v153, s53
	v_lshlrev_b32_e32 v184, 4, v154
	v_cndmask_b32_e32 v8, v9, v8, vcc
	v_mul_f32_e32 v8, v174, v8
	v_cmp_ge_f32_e32 vcc, s52, v8
	v_add3_u32 v8, 0, v178, v179
	ds_write_b128 v8, v[96:99]
	v_add3_u32 v8, 0, v181, v182
	ds_write_b128 v8, v[100:103]
	v_add3_u32 v8, 0, v183, v184
	v_mul_lo_u32 v185, v68, s56
	ds_write_b128 v8, v[104:107]
	v_add_u32_e32 v8, 0, v185
	v_and_b32_e32 v186, 1, v69
	v_lshlrev_b32_e32 v186, 3, v186
	v_sub_u32_e32 v186, 0, v186
	v_lshl_add_u32 v186, v69, 4, v186
	v_add3_u32 v8, v8, v186, s57
	v_mul_lo_u32 v187, v74, s56
	ds_write2_b64 v8, v[108:109], v[110:111] offset1:2
	v_add_u32_e32 v8, 0, v187
	v_and_b32_e32 v188, 1, v75
	v_lshlrev_b32_e32 v188, 3, v188
	v_sub_u32_e32 v188, 0, v188
	v_lshl_add_u32 v188, v75, 4, v188
	v_and_b32_e32 v10, 31, v155
	v_add3_u32 v8, v8, v188, s57
	s_ashr_i32 s27, s26, 31
	s_and_b32 s69, s39, 0xffffffe0
	ds_write2_b64 v8, v[112:113], v[114:115] offset1:2
	v_mul_u32_u24_e32 v8, 0x110, v10
	s_cmp_lg_u64 vcc, exec
	v_add3_u32 v191, v0, v8, v0
	v_lshl_add_u64 v[8:9], s[22:23], 0, v[70:71]
	s_cselect_b64 s[2:3], -1, 0
	s_add_i32 s69, s69, s38
	v_lshl_add_u64 v[164:165], v[72:73], 1, v[8:9]
	v_lshl_add_u64 v[8:9], s[22:23], 0, v[64:65]
	v_lshl_add_u64 v[6:7], s[24:25], 0, v[6:7]
	v_lshl_add_u64 v[4:5], s[24:25], 0, v[4:5]
	v_lshl_add_u64 v[2:3], s[24:25], 0, v[2:3]
	v_mov_b32_e32 v14, v1
	v_mov_b32_e32 v15, v1
	v_or_b32_e32 v189, s69, v10
	v_mul_u32_u24_e32 v192, 0xd0, v10
	v_lshl_add_u64 v[166:167], v[66:67], 1, v[8:9]
	v_lshl_add_u64 v[168:169], v[62:63], 1, v[6:7]
	v_lshl_add_u64 v[170:171], v[60:61], 1, v[4:5]
	v_lshl_add_u64 v[172:173], v[58:59], 1, v[2:3]
	v_lshl_add_u64 v[164:165], s[4:5], 0, v[164:165]
	v_lshl_add_u64 v[166:167], s[4:5], 0, v[166:167]
	v_lshl_add_u64 v[168:169], s[4:5], 0, v[168:169]
	v_lshl_add_u64 v[170:171], s[4:5], 0, v[170:171]
	v_lshl_add_u64 v[172:173], s[4:5], 0, v[172:173]
	s_nop 0
	s_nop 0
	s_nop 0
	s_nop 0
	s_nop 0
	s_nop 0
	s_nop 0
	s_nop 0
	v_mov_b32_e32 v0, v1
	v_mov_b32_e32 v2, v1
	v_mov_b32_e32 v3, v1
	v_mov_b32_e32 v4, v1
	v_mov_b32_e32 v5, v1
	v_mov_b32_e32 v6, v1
	v_mov_b32_e32 v7, v1
	v_mov_b32_e32 v8, v1
	v_mov_b32_e32 v9, v1
	v_mov_b32_e32 v10, v1
	v_mov_b32_e32 v11, v1
	v_mov_b32_e32 v12, v1
	v_mov_b32_e32 v13, v1
	v_mov_b64_e32 v[30:31], v[14:15]
	v_mov_b64_e32 v[46:47], v[14:15]
	v_mov_b64_e32 v[62:63], v[14:15]
	s_mov_b32 s12, 0
	s_or_b32 s70, s69, 31
	v_lshl_add_u32 v190, v148, 4, 0
	v_lshlrev_b32_e32 v180, 2, v148
	s_mov_b64 s[40:41], -1
	v_mov_b32_e32 v193, 0
	s_mov_b32 s71, 63
	v_mov_b64_e32 v[28:29], v[12:13]
	v_mov_b64_e32 v[26:27], v[10:11]
	v_mov_b64_e32 v[24:25], v[8:9]
	v_mov_b64_e32 v[22:23], v[6:7]
	v_mov_b64_e32 v[20:21], v[4:5]
	v_mov_b64_e32 v[18:19], v[2:3]
	v_mov_b64_e32 v[16:17], v[0:1]
	v_mov_b64_e32 v[44:45], v[12:13]
	v_mov_b64_e32 v[42:43], v[10:11]
	v_mov_b64_e32 v[40:41], v[8:9]
	v_mov_b64_e32 v[38:39], v[6:7]
	v_mov_b64_e32 v[36:37], v[4:5]
	v_mov_b64_e32 v[34:35], v[2:3]
	v_mov_b64_e32 v[32:33], v[0:1]
	v_mov_b64_e32 v[60:61], v[12:13]
	v_mov_b64_e32 v[58:59], v[10:11]
	v_mov_b64_e32 v[56:57], v[8:9]
	v_mov_b64_e32 v[54:55], v[6:7]
	v_mov_b64_e32 v[52:53], v[4:5]
	v_mov_b64_e32 v[50:51], v[2:3]
	v_mov_b64_e32 v[48:49], v[0:1]
	v_mov_b32_e32 v0, 0
	s_waitcnt lgkmcnt(0)
	s_barrier

; #define LAS __attribute__((address_space(3)))
; template <int DQK, int DV, bool CAUSAL, int KT, bool PRIO>
; DI void attn_unit(const bf16_t* Qb, int qpitch, const bf16_t* Kb, int kpitch, const bf16_t* Vtb, int vpitch, bf16_t* Ob, int opitch, int q0, int nt, LAS unsigned char* lds, float kbound, const float* qgain, const int* qpos, float qscale) {
;     ...
;     auto lstore = [&](int buf) {
; #pragma unroll
;         for (int i = 0; i < NKR; ++i) { const int c = tid + i * 512; if (NKC % 512 == 0 || c < NKC) *(LAS u32x4*)(lds + buf * KBUF + (c / KCH) * KS + (c % KCH) * 16) = kreg[i]; }
; #pragma unroll
;         for (int i = 0; i < NVR; ++i) { const int c = tid + i * 512; LAS unsigned char* p = lds + VOFF + buf * VBUF + (c / VCH) * VS + (c % VCH) * 16;
;             *(LAS u32x2*)p = (u32x2){vreg[i].x, vreg[i].y}; *(LAS u32x2*)(p + 8) = (u32x2){vreg[i].z, vreg[i].w}; }
;     ...
;                     float ps = 0.f;
; #pragma unroll
;                     for (int i = 0; i < 16; ++i) { s0[i] = __builtin_amdgcn_exp2f(s0[i]); ps += s0[i]; asm volatile("" : "+v"(ps)); }
; #pragma unroll
;                     for (int i = 0; i < 16; ++i) { s1[i] = __builtin_amdgcn_exp2f(s1[i]); ps += s1[i]; asm volatile("" : "+v"(ps)); }
;                     lrun += ps;
;                     bf16x8 pf[4];
; #pragma unroll
;                     for (int sf = 0; sf < 2; ++sf) {
;                         u32x4 pw; pw.x = pk2(s0[8 * sf], s0[8 * sf + 1]); pw.y = pk2(s0[8 * sf + 2], s0[8 * sf + 3]); pw.z = pk2(s0[8 * sf + 4], s0[8 * sf + 5]); pw.w = pk2(s0[8 * sf + 6], s0[8 * sf + 7]); pf[sf] = __builtin_bit_cast(bf16x8, pw);
;                         u32x4 pv; pv.x = pk2(s1[8 * sf], s1[8 * sf + 1]); pv.y = pk2(s1[8 * sf + 2], s1[8 * sf + 3]); pv.z = pk2(s1[8 * sf + 4], s1[8 * sf + 5]); pv.w = pk2(s1[8 * sf + 6], s1[8 * sf + 7]); pf[2 + sf] = __builtin_bit_cast(bf16x8, pv);
;                     }
;                     __builtin_amdgcn_sched_barrier(0); __builtin_amdgcn_s_setprio(1); __builtin_amdgcn_sched_barrier(0);
; #pragma unroll
;                     for (int q4 = 0; q4 < 4; ++q4)
; #pragma unroll
;                         for (int d = 0; d < NDB; ++d) o[d] = MFMA32(vf[q4][d], pf[q4], o[d]);
;                     __builtin_amdgcn_sched_barrier(0); __builtin_amdgcn_s_setprio(0); __builtin_amdgcn_sched_barrier(0);
.LBB0_1514:
	s_nop 7
	v_exp_f32_e32 v14, v80
	v_exp_f32_e32 v15, v81
	v_exp_f32_e32 v80, v82
	v_exp_f32_e32 v81, v83
	v_add_f32_e32 v82, 0, v14
	v_exp_f32_e32 v83, v84
	v_add_f32_e32 v82, v15, v82
	v_exp_f32_e32 v84, v85
	v_add_f32_e32 v82, v80, v82
	v_exp_f32_e32 v85, v86
	v_add_f32_e32 v82, v81, v82
	v_exp_f32_e32 v86, v87
	v_add_f32_e32 v82, v83, v82
	v_exp_f32_e32 v87, v88
	v_add_f32_e32 v82, v84, v82
	v_exp_f32_e32 v88, v89
	v_add_f32_e32 v82, v85, v82
	v_exp_f32_e32 v89, v90
	v_add_f32_e32 v82, v86, v82
	v_exp_f32_e32 v90, v91
	v_add_f32_e32 v82, v87, v82
	v_exp_f32_e32 v91, v92
	v_add_f32_e32 v82, v88, v82
	v_exp_f32_e32 v92, v93
	v_add_f32_e32 v82, v89, v82
	v_exp_f32_e32 v93, v94
	v_add_f32_e32 v82, v90, v82
	v_exp_f32_e32 v94, v95
	v_add_f32_e32 v82, v91, v82
	v_exp_f32_e32 v95, v64
	v_add_f32_e32 v82, v92, v82
	v_exp_f32_e32 v194, v66
	v_add_f32_e32 v82, v93, v82
	v_exp_f32_e32 v195, v67
	v_add_f32_e32 v64, v94, v82
	v_exp_f32_e32 v82, v65
	v_exp_f32_e32 v197, v68
	v_add_f32_e32 v64, v95, v64
	v_exp_f32_e32 v198, v69
	v_add_f32_e32 v64, v82, v64
	v_exp_f32_e32 v199, v70
	v_add_f32_e32 v64, v194, v64
	v_exp_f32_e32 v71, v71
	v_add_f32_e32 v64, v195, v64
	v_exp_f32_e32 v200, v72
	v_add_f32_e32 v64, v197, v64
	v_exp_f32_e32 v201, v73
	v_add_f32_e32 v64, v198, v64
	v_exp_f32_e32 v202, v74
	v_add_f32_e32 v64, v199, v64
	v_exp_f32_e32 v203, v75
	v_add_f32_e32 v64, v71, v64
	v_exp_f32_e32 v204, v76
	v_add_f32_e32 v64, v200, v64
	v_exp_f32_e32 v205, v77
	v_add_f32_e32 v64, v201, v64
	v_exp_f32_e32 v206, v78
	v_add_f32_e32 v64, v202, v64
	v_exp_f32_e32 v79, v79
	v_add_f32_e32 v64, v203, v64
	v_cvt_pk_bf16_f32 v65, v80, v81
	v_add_f32_e32 v64, v204, v64
	v_cvt_pk_bf16_f32 v66, v83, v84
	v_add_f32_e32 v64, v205, v64
	v_cvt_pk_bf16_f32 v67, v85, v86
	v_add_f32_e32 v64, v206, v64
	v_cvt_pk_bf16_f32 v68, v95, v82
	v_add_f32_e32 v207, v79, v64
	v_cvt_pk_bf16_f32 v64, v14, v15
	v_cvt_pk_bf16_f32 v69, v194, v195
	v_cvt_pk_bf16_f32 v70, v197, v198
	v_cvt_pk_bf16_f32 v71, v199, v71
	v_cvt_pk_bf16_f32 v72, v87, v88
	v_cvt_pk_bf16_f32 v73, v89, v90
	v_cvt_pk_bf16_f32 v74, v91, v92
	v_cvt_pk_bf16_f32 v75, v93, v94
	v_cvt_pk_bf16_f32 v76, v200, v201
	v_cvt_pk_bf16_f32 v77, v202, v203
	v_cvt_pk_bf16_f32 v78, v204, v205
	v_cvt_pk_bf16_f32 v79, v206, v79
	s_setprio 1
	s_waitcnt lgkmcnt(0)
	s_waitcnt vmcnt(0)
	v_mfma_f32_32x32x16_bf16 v[32:47], v[156:159], v[64:67], v[32:47]
	v_add_f32_e32 v0, v0, v207
	s_xor_b32 s100, s75, 1
	s_mul_i32 s101, s100, 0x6800
	v_add3_u32 v250, s101, v178, v179
	v_mfma_f32_32x32x16_bf16 v[16:31], v[152:155], v[64:67], v[16:31]
	ds_write_b128 v250, v[96:99]
	v_add3_u32 v251, s101, v181, v182
	s_mulk_i32 s100, 0xdc00
	v_mfma_f32_32x32x16_bf16 v[32:47], v[140:143], v[72:75], v[32:47]
	ds_write_b128 v251, v[100:103]
	v_add3_u32 v250, s101, v183, v184
	s_add_i32 s101, s101, s100
	v_mfma_f32_32x32x16_bf16 v[16:31], v[148:151], v[72:75], v[16:31]
	ds_write_b128 v250, v[104:107]
	v_add_u32_e32 v251, s101, v185
	v_add3_u32 v251, v251, v186, s57
	v_mfma_f32_32x32x16_bf16 v[32:47], v[144:147], v[68:71], v[32:47]
	ds_write2_b64 v251, v[108:109], v[110:111] offset1:2
	v_add_u32_e32 v250, s101, v187
	v_add3_u32 v250, v250, v188, s57
	v_mfma_f32_32x32x16_bf16 v[16:31], v[10:13], v[68:71], v[16:31]
	ds_write2_b64 v250, v[112:113], v[114:115] offset1:2
	v_mfma_f32_32x32x16_bf16 v[32:47], v[6:9], v[76:79], v[32:47]
	v_mfma_f32_32x32x16_bf16 v[16:31], v[2:5], v[76:79], v[16:31]
	s_setprio 0
	s_branch .LBB0_1493
	s_nop 0
	s_nop 0
	s_nop 0
	s_nop 0
	s_nop 0
	s_nop 0
	s_nop 0
	s_nop 0
	s_nop 0
	s_nop 0
	s_nop 0
.LBB0_1515:
	s_branch .LBB0_1503
